# one static s_setprio 1 for the younger half (waves 4-7) during the attention phase
# baseline (speedup 1.0000x reference)
; __device__ __forceinline__ size_t tmo(int row, int ct, int nct) { return ((size_t)(row >> 8) * nct + ct) * 32768 + (size_t)(row & 255) * 128; }
; __device__ __forceinline__ void attn_a_prefetch(const bf16* Z, int unit, v4u (&kr)[7], v4u (&vr)[7]) {
;     const int tid = threadIdx.x; const int ib = unit & 63, kvh = (unit >> 6) & 1, b = unit >> 7;
;     const size_t tok0 = (size_t)b * SEQ; const int kstart = (ib - 1) * 128;
; #pragma unroll
;     for (int k = 0; k < 7; ++k) { const int it = tid + k * NTHREADS; const int row = it >> 3, ch = it & 7, pos = kstart + row;
;         kr[k] = (v4u){0u, 0u, 0u, 0u}; vr[k] = (v4u){0u, 0u, 0u, 0u};
;         if (it < A_ROWS * 8 && row < 384 && pos >= 0 && pos < SEQ) { const int t = (int)tok0 + pos; kr[k] = *(const v4u*)((const unsigned char*)Z + tmo(t, Z_KA / 64 + kvh, ZLD / 64) + ch * 16); vr[k] = *(const v4u*)((const unsigned char*)Z + tmo(t, Z_VA / 64 + kvh, ZLD / 64) + ch * 16); } }
; __global__ void __launch_bounds__(NTHREADS, 2) mk_fwd(Args args) {
;     ...
;     if (IN(2)) {
;         {
;             v4u kr[7], vr[7]; int u = vcu; const int NU = BATCH * 2 * 64;
;             if (u < NU) attn_a_prefetch(Zb, u, kr, vr);
.LBB0_224:
.LBB0_225:
	s_cmp_lt_i32 s34, 3
	s_cselect_b64 s[0:1], -1, 0
	s_add_u32 s40, s30, 0xa000000
	s_addc_u32 s41, s31, 0
	s_and_b64 s[48:49], s[0:1], s[4:5]
	s_andn2_b64 vcc, exec, s[48:49]
	s_cbranch_vccnz .LBB0_294
	v_readfirstlane_b32 s90, v218
	s_nop 3
	s_lshr_b32 s90, s90, 6
	s_cmp_ge_u32 s90, 4
	s_cbranch_scc0 .Lp2_prio_done
	s_setprio 1
.Lp2_prio_done:
	v_mov_b32_e32 v49, 0
	s_cmpk_lt_i32 s96, 0x400
	s_cselect_b64 s[6:7], -1, 0
	s_cmpk_gt_i32 s96, 0x3ff
	v_mov_b32_e32 v48, v49
	v_mov_b32_e32 v47, v49
	v_mov_b32_e32 v46, v49
	v_mov_b32_e32 v45, v49
	v_mov_b32_e32 v44, v49
	v_mov_b32_e32 v43, v49
	v_mov_b32_e32 v42, v49
	v_mov_b32_e32 v29, v49
	v_mov_b32_e32 v28, v49
	v_mov_b32_e32 v27, v49
	v_mov_b32_e32 v26, v49
	v_mov_b32_e32 v21, v49
	v_mov_b32_e32 v20, v49
	v_mov_b32_e32 v19, v49
	v_mov_b32_e32 v18, v49
	v_mov_b32_e32 v17, v49
	v_mov_b32_e32 v16, v49
	v_mov_b32_e32 v15, v49
	v_mov_b32_e32 v14, v49
	v_mov_b32_e32 v9, v49
	v_mov_b32_e32 v8, v49
	v_mov_b32_e32 v7, v49
	v_mov_b32_e32 v6, v49
	v_mov_b32_e32 v41, v49
	v_mov_b32_e32 v40, v49
	v_mov_b32_e32 v39, v49
	v_mov_b32_e32 v38, v49
	v_mov_b32_e32 v37, v49
	v_mov_b32_e32 v36, v49
	v_mov_b32_e32 v35, v49
	v_mov_b32_e32 v34, v49
	v_mov_b32_e32 v33, v49
	v_mov_b32_e32 v32, v49
	v_mov_b32_e32 v31, v49
	v_mov_b32_e32 v30, v49
	v_mov_b32_e32 v25, v49
	v_mov_b32_e32 v24, v49
	v_mov_b32_e32 v23, v49
	v_mov_b32_e32 v22, v49
	v_mov_b32_e32 v5, v49
	v_mov_b32_e32 v4, v49
	v_mov_b32_e32 v3, v49
	v_mov_b32_e32 v2, v49
	v_mov_b32_e32 v13, v49
	v_mov_b32_e32 v12, v49
	v_mov_b32_e32 v11, v49
	v_mov_b32_e32 v10, v49
	s_cbranch_scc1 .LBB0_238
	s_lshl_b32 s1, s96, 7
	s_bfe_u32 s3, s96, 0x10006
	s_lshl_b32 s0, s96, 6
	s_and_b32 s1, s1, 0x1f80
	v_lshlrev_b32_e32 v2, 4, v218
	s_and_b32 s0, s0, 0xffffe000
	s_addk_i32 s1, 0xff80
	s_or_b32 s10, s3, 8
	s_mov_b32 s11, 0
	v_and_b32_e32 v50, 0x70, v2
	v_mov_b32_e32 v2, 0
	s_or_b32 s8, s3, 10
	v_mov_b32_e32 v51, v2
	s_mov_b32 s9, s11
	s_cmpk_gt_u32 s1, 0x1fff
	v_mov_b32_e32 v10, 0
	v_mov_b32_e32 v11, 0
	v_mov_b32_e32 v12, 0
	v_mov_b32_e32 v13, 0
	v_mov_b32_e32 v6, 0
	v_mov_b32_e32 v7, 0
	v_mov_b32_e32 v8, 0
	v_mov_b32_e32 v9, 0
	s_cbranch_scc1 .LBB0_229
	s_or_b32 s3, s1, s0
	s_ashr_i32 s3, s3, 8
	s_mulk_i32 s3, 0x44
	s_ashr_i32 s12, s3, 31
	s_add_u32 s4, s3, s10
	v_lshrrev_b32_e32 v3, 3, v218
	s_addc_u32 s5, s12, 0
	v_or_b32_e32 v3, s1, v3
	s_lshl_b64 s[4:5], s[4:5], 15
	v_lshlrev_b32_e32 v3, 7, v3
	s_add_u32 s4, s38, s4
	v_and_b32_e32 v4, 0x7f80, v3
	v_mov_b32_e32 v5, 0
	s_addc_u32 s5, s39, s5
	v_lshl_add_u64 v[6:7], s[4:5], 0, v[4:5]
	s_add_u32 s4, s3, s8
	s_addc_u32 s5, s12, 0
	s_lshl_b64 s[4:5], s[4:5], 15
	s_add_u32 s4, s38, s4
	s_addc_u32 s5, s39, s5
	v_lshl_add_u64 v[6:7], v[6:7], 0, v[50:51]
	v_lshl_add_u64 v[4:5], s[4:5], 0, v[4:5]
	v_lshl_add_u64 v[4:5], v[4:5], 0, v[50:51]
	global_load_dwordx4 v[6:9], v[6:7], off
	s_nop 0
	global_load_dwordx4 v[10:13], v[4:5], off

; __device__ __forceinline__ unsigned xb_ld(unsigned* p)              { return __hip_atomic_load(p, __ATOMIC_RELAXED, __HIP_MEMORY_SCOPE_AGENT); }
; __device__ __forceinline__ unsigned xb_add(unsigned* p, unsigned v) { return __hip_atomic_fetch_add(p, v, __ATOMIC_RELAXED, __HIP_MEMORY_SCOPE_AGENT); }
; __device__ __forceinline__ void xcd_barrier_complete(unsigned* bar, unsigned x, unsigned& nloc, unsigned& nx) {
;     const unsigned G = gridDim.x * gridDim.y * gridDim.z;
;     unsigned sum, cnt, mine, sp = 0u;
;     for (;;) {
;         sum = 0u; cnt = 0u; mine = 0u;
; #pragma unroll
;         for (unsigned j = 0; j < 16; ++j) { const unsigned c = xb_ld(&bar[XB_XCNT(j)]); sum += c; cnt += (c > 0u) ? 1u : 0u; mine = (j == x) ? c : mine; }
; __device__ __forceinline__ void xcd_barrier(const XcdBarrier& b) {
;     asm volatile("s_waitcnt vmcnt(0)" ::: "memory");
;     __syncthreads();
;     if (threadIdx.x == 0) {
;         unsigned* bar = b.bar;
;         __builtin_amdgcn_s_waitcnt(0);
;         unsigned nloc = b.st[0], nx = b.st[1];
;         if (nloc == 0u) { xcd_barrier_complete(bar, b.x, nloc, nx); b.st[0] = nloc; b.st[1] = nx; }
;         const unsigned old = xb_add(&bar[XB_XSUB(b.x)], 1u);
.LBB0_294:
	s_setprio 0
	s_cmp_gt_i32 s35, 3
	s_cselect_b64 s[4:5], -1, 0
	s_and_b64 s[0:1], s[48:49], s[4:5]
	s_andn2_b64 vcc, exec, s[0:1]
	s_cbranch_vccnz .LBB0_362
	s_cmp_lt_u32 s35, 9
	s_mov_b64 s[6:7], -1
	s_cbranch_scc0 .LBB0_349
	s_waitcnt vmcnt(0)
	s_waitcnt vmcnt(0)
	s_barrier
	s_mov_b64 s[6:7], exec
	v_readlane_b32 s0, v246, 5
	v_readlane_b32 s1, v246, 6
	s_and_b64 s[0:1], s[6:7], s[0:1]
	s_mov_b64 exec, s[0:1]
	s_cbranch_execz .LBB0_348
	s_add_i32 s0, 0, 0x25ff0
	v_mov_b32_e32 v2, s0
	s_waitcnt vmcnt(0) expcnt(0) lgkmcnt(0)
	ds_read_b32 v4, v2
	s_add_i32 s0, 0, 0x25ff4
	v_mov_b32_e32 v2, s0
	ds_read_b32 v2, v2
	s_waitcnt lgkmcnt(1)
	v_cmp_ne_u32_e32 vcc, 0, v4
	s_cbranch_vccnz .LBB0_312
	v_readlane_b32 s8, v246, 0
	v_readlane_b32 s9, v246, 1
	s_load_dwordx2 s[0:1], s[8:9], 0x4
	s_add_u32 s8, s30, 0xc0200
	s_addc_u32 s9, s31, 0
	s_add_u32 s10, s30, 0xc0400
	s_addc_u32 s11, s31, 0
	s_add_u32 s12, s30, 0xc0500
	s_addc_u32 s13, s31, 0
	s_add_u32 s14, s30, 0xc0600
	s_addc_u32 s15, s31, 0
	s_add_u32 s16, s30, 0xc0700
	s_addc_u32 s17, s31, 0
	s_add_u32 s18, s30, 0xc0800
	s_addc_u32 s19, s31, 0
	s_add_u32 s20, s30, 0xc0900
	s_addc_u32 s21, s31, 0
	s_add_u32 s22, s30, 0xc0a00
	s_addc_u32 s23, s31, 0
	s_add_u32 s24, s30, 0xc0b00
	s_addc_u32 s25, s31, 0
	s_add_u32 s26, s30, 0xc0c00
	s_addc_u32 s27, s31, 0
	s_add_u32 s28, s30, 0xc0d00
	s_addc_u32 s29, s31, 0
	s_add_u32 s44, s30, 0xc0e00
	s_addc_u32 s45, s31, 0
	s_add_u32 s46, s30, 0xc0f00
	s_addc_u32 s47, s31, 0
	s_add_u32 s48, s30, 0xc1000
	s_addc_u32 s49, s31, 0
	s_add_u32 s50, s30, 0xc1100
	s_addc_u32 s51, s31, 0
	s_add_u32 s70, s30, 0xc1200
	s_addc_u32 s71, s31, 0
	s_waitcnt lgkmcnt(0)
	s_mul_i32 s0, s0, s33
	s_add_u32 s72, s30, 0xc1300
	s_mul_i32 s0, s0, s1
	s_addc_u32 s73, s31, 0
	s_mov_b32 s1, 1
	v_mov_b32_e32 v18, 0
	s_branch .LBB0_300
